# out-proj epilogue residual loads without the nt hint (plain loads) on the all-to-all release version
# speedup vs baseline: 1.0119x; 1.0080x over previous
; #define LAS __attribute__((address_space(3)))
; __device__ __forceinline__ int crow(int r, int hi) { return (r & 3) + 8 * (r >> 2) + 4 * hi; }
; __device__ __forceinline__ void g2_sample_tile(const bf16_t* __restrict__ Y, const bf16_t* __restrict__ Wt, const float* xs  , const bf16_t* xbs  , float* outs  , bf16_t* outbs  , const float* __restrict__ gate, ...
;     ...
;     const bf16_t* ap = Y + (size_t)(MP + row0 + m) * D + wave * 128 + kq * 8;
;     const bf16_t* bp = Wt + (size_t)(col0 + m) * D + wave * 128 + kq * 8;
; #pragma unroll
;     for (int ks = 0; ks < 8; ++ks) {
;         const bf16x8 a0 = *(const bf16x8*)(ap + ks * 16), a1 = *(const bf16x8*)(ap + 32 * D + ks * 16), b0 = *(const bf16x8*)(bp + ks * 16), b1 = *(const bf16x8*)(bp + 32 * D + ks * 16);
;         acc[0][0] = __builtin_amdgcn_mfma_f32_32x32x16_bf16(a0, b0, acc[0][0], 0, 0, 0); acc[0][1] = __builtin_amdgcn_mfma_f32_32x32x16_bf16(a0, b1, acc[0][1], 0, 0, 0);
;         acc[1][0] = __builtin_amdgcn_mfma_f32_32x32x16_bf16(a1, b0, acc[1][0], 0, 0, 0); acc[1][1] = __builtin_amdgcn_mfma_f32_32x32x16_bf16(a1, b1, acc[1][1], 0, 0, 0);
;     }
;     LAS float* slab = (LAS float*)lds + wave * 4096;
; #pragma unroll
;     for (int i2 = 0; i2 < 2; ++i2)
; #pragma unroll
;         for (int j2 = 0; j2 < 2; ++j2)
; #pragma unroll
;             for (int i = 0; i < 16; ++i) slab[(32 * i2 + crow(i, kq)) * 64 + 32 * j2 + m] = acc[i2][j2][i];
;     __syncthreads();
.LBB0_594:
	s_and_b32 s21, s23, 0xffffffc0
	v_add_u32_e32 v0, s21, v78
	v_ashrrev_i32_e32 v1, 31, v0
	s_and_b32 s20, s22, 0x3c0
	v_lshlrev_b64 v[0:1], 11, v[0:1]
	v_lshl_add_u64 v[72:73], v[64:65], 0, v[0:1]
	v_or_b32_e32 v0, s20, v69
	v_lshlrev_b32_e32 v172, 11, v0
	global_load_dwordx4 v[0:3], v[72:73], off
	v_add_co_u32_e32 v74, vcc, 0x10000, v72
	v_lshl_add_u64 v[70:71], v[66:67], 0, v[172:173]
	s_nop 0
	v_addc_co_u32_e32 v75, vcc, 0, v73, vcc
	v_add_co_u32_e32 v76, vcc, 0x10000, v70
	global_load_dwordx4 v[16:19], v[74:75], off
	global_load_dwordx4 v[4:7], v[70:71], off
	v_addc_co_u32_e32 v77, vcc, 0, v71, vcc
	global_load_dwordx4 v[20:23], v[76:77], off
	global_load_dwordx4 v[90:93], v[72:73], off offset:32
	global_load_dwordx4 v[94:97], v[74:75], off offset:32
	global_load_dwordx4 v[98:101], v[70:71], off offset:32
	global_load_dwordx4 v[102:105], v[76:77], off offset:32
	global_load_dwordx4 v[106:109], v[72:73], off offset:64
	global_load_dwordx4 v[110:113], v[74:75], off offset:64
	global_load_dwordx4 v[114:117], v[70:71], off offset:64
	global_load_dwordx4 v[118:121], v[76:77], off offset:64
	global_load_dwordx4 v[122:125], v[72:73], off offset:96
	global_load_dwordx4 v[126:129], v[74:75], off offset:96
	global_load_dwordx4 v[132:135], v[70:71], off offset:96
	global_load_dwordx4 v[136:139], v[76:77], off offset:96
	global_load_dwordx4 v[140:143], v[72:73], off offset:128
	global_load_dwordx4 v[144:147], v[74:75], off offset:128
	global_load_dwordx4 v[148:151], v[70:71], off offset:128
	global_load_dwordx4 v[152:155], v[76:77], off offset:128
	global_load_dwordx4 v[156:159], v[72:73], off offset:160
	global_load_dwordx4 v[160:163], v[74:75], off offset:160
	global_load_dwordx4 v[164:167], v[70:71], off offset:160
	global_load_dwordx4 v[168:171], v[76:77], off offset:160
	global_load_dwordx4 v[182:185], v[72:73], off offset:192
	global_load_dwordx4 v[186:189], v[74:75], off offset:192
	global_load_dwordx4 v[190:193], v[70:71], off offset:192
	global_load_dwordx4 v[194:197], v[76:77], off offset:192
	global_load_dwordx4 v[198:201], v[72:73], off offset:224
	global_load_dwordx4 v[202:205], v[74:75], off offset:224
	global_load_dwordx4 v[236:239], v[70:71], off offset:224
	global_load_dwordx4 v[240:243], v[76:77], off offset:224
	s_lshl_b32 s86, s20, 2
	v_lshlrev_b32_e32 v172, 2, v68
	s_waitcnt vmcnt(29)
	v_mfma_f32_32x32x16_bf16 v[32:47], v[0:3], v[4:7], 0
	s_waitcnt vmcnt(28)
	v_mfma_f32_32x32x16_bf16 v[48:63], v[0:3], v[20:23], 0
	v_mfma_f32_32x32x16_bf16 v[0:15], v[16:19], v[4:7], 0
	v_mfma_f32_32x32x16_bf16 v[16:31], v[16:19], v[20:23], 0
	s_waitcnt vmcnt(24)
	v_mfma_f32_32x32x16_bf16 v[32:47], v[90:93], v[98:101], v[32:47]
	v_mfma_f32_32x32x16_bf16 v[48:63], v[90:93], v[102:105], v[48:63]
	v_mfma_f32_32x32x16_bf16 v[0:15], v[94:97], v[98:101], v[0:15]
	v_mfma_f32_32x32x16_bf16 v[16:31], v[94:97], v[102:105], v[16:31]
	s_waitcnt vmcnt(20)
	v_mfma_f32_32x32x16_bf16 v[32:47], v[106:109], v[114:117], v[32:47]
	v_mfma_f32_32x32x16_bf16 v[48:63], v[106:109], v[118:121], v[48:63]
	v_mfma_f32_32x32x16_bf16 v[0:15], v[110:113], v[114:117], v[0:15]
	v_mfma_f32_32x32x16_bf16 v[16:31], v[110:113], v[118:121], v[16:31]
	s_waitcnt vmcnt(16)
	v_mfma_f32_32x32x16_bf16 v[32:47], v[122:125], v[132:135], v[32:47]
	v_mfma_f32_32x32x16_bf16 v[48:63], v[122:125], v[136:139], v[48:63]
	v_mfma_f32_32x32x16_bf16 v[0:15], v[126:129], v[132:135], v[0:15]
	v_mfma_f32_32x32x16_bf16 v[16:31], v[126:129], v[136:139], v[16:31]
	s_waitcnt vmcnt(12)
	v_mfma_f32_32x32x16_bf16 v[32:47], v[140:143], v[148:151], v[32:47]
	v_mfma_f32_32x32x16_bf16 v[48:63], v[140:143], v[152:155], v[48:63]
	v_mfma_f32_32x32x16_bf16 v[0:15], v[144:147], v[148:151], v[0:15]
	v_mfma_f32_32x32x16_bf16 v[16:31], v[144:147], v[152:155], v[16:31]
	s_waitcnt vmcnt(8)
	v_mfma_f32_32x32x16_bf16 v[32:47], v[156:159], v[164:167], v[32:47]
	v_mfma_f32_32x32x16_bf16 v[48:63], v[156:159], v[168:171], v[48:63]
	v_mfma_f32_32x32x16_bf16 v[0:15], v[160:163], v[164:167], v[0:15]
	v_mfma_f32_32x32x16_bf16 v[16:31], v[160:163], v[168:171], v[16:31]
	s_waitcnt vmcnt(4)
	v_mfma_f32_32x32x16_bf16 v[32:47], v[182:185], v[190:193], v[32:47]
	v_mfma_f32_32x32x16_bf16 v[48:63], v[182:185], v[194:197], v[48:63]
	v_mfma_f32_32x32x16_bf16 v[0:15], v[186:189], v[190:193], v[0:15]
	v_mfma_f32_32x32x16_bf16 v[16:31], v[186:189], v[194:197], v[16:31]
	s_waitcnt vmcnt(0)
	v_mfma_f32_32x32x16_bf16 v[32:47], v[198:201], v[236:239], v[32:47]
	v_mfma_f32_32x32x16_bf16 v[48:63], v[198:201], v[240:243], v[48:63]
	s_nop 11
	ds_write2_b32 v79, v32, v48 offset1:32
	ds_write2_b32 v79, v33, v49 offset0:64 offset1:96
	ds_write2_b32 v79, v34, v50 offset0:128 offset1:160
	ds_write2_b32 v79, v35, v51 offset0:192 offset1:224
	v_mfma_f32_32x32x16_bf16 v[0:15], v[202:205], v[236:239], v[0:15]
	v_add_u32_e32 v32, 0x800, v79
	ds_write2_b32 v32, v36, v52 offset1:32
	ds_write2_b32 v32, v37, v53 offset0:64 offset1:96
	ds_write2_b32 v32, v38, v54 offset0:128 offset1:160
	ds_write2_b32 v32, v39, v55 offset0:192 offset1:224
	v_add_u32_e32 v32, 0x1000, v79
	ds_write2_b32 v32, v40, v56 offset1:32
	ds_write2_b32 v32, v41, v57 offset0:64 offset1:96
	ds_write2_b32 v32, v42, v58 offset0:128 offset1:160
	ds_write2_b32 v32, v43, v59 offset0:192 offset1:224
	v_add_u32_e32 v32, 0x1800, v79
	ds_write2_b32 v32, v44, v60 offset1:32
	ds_write2_b32 v32, v45, v61 offset0:64 offset1:96
	ds_write2_b32 v32, v46, v62 offset0:128 offset1:160
	ds_write2_b32 v32, v47, v63 offset0:192 offset1:224
	v_add_u32_e32 v32, 0x2000, v79
	v_mfma_f32_32x32x16_bf16 v[16:31], v[202:205], v[240:243], v[16:31]
	s_nop 11
	ds_write2_b32 v32, v0, v16 offset1:32
	ds_write2_b32 v32, v1, v17 offset0:64 offset1:96
	ds_write2_b32 v32, v2, v18 offset0:128 offset1:160
	ds_write2_b32 v32, v3, v19 offset0:192 offset1:224
	v_add_u32_e32 v0, 0x2800, v79
	ds_write2_b32 v0, v4, v20 offset1:32
	ds_write2_b32 v0, v5, v21 offset0:64 offset1:96
	ds_write2_b32 v0, v6, v22 offset0:128 offset1:160
	ds_write2_b32 v0, v7, v23 offset0:192 offset1:224
	v_add_u32_e32 v0, 0x3000, v79
	ds_write2_b32 v0, v8, v24 offset1:32
	ds_write2_b32 v0, v9, v25 offset0:64 offset1:96
	ds_write2_b32 v0, v10, v26 offset0:128 offset1:160
	ds_write2_b32 v0, v11, v27 offset0:192 offset1:224
	v_add_u32_e32 v0, 0x3800, v79
	ds_write2_b32 v0, v12, v28 offset1:32
	ds_write2_b32 v0, v13, v29 offset0:64 offset1:96
	ds_write2_b32 v0, v14, v30 offset0:128 offset1:160
	ds_write2_b32 v0, v15, v31 offset0:192 offset1:224
	s_waitcnt lgkmcnt(0)
	s_barrier
; #define LAS __attribute__((address_space(3)))
; __device__ __forceinline__ void g2_sample_tile(const bf16_t* __restrict__ Y, const bf16_t* __restrict__ Wt, const float* xs  , const bf16_t* xbs  , float* outs  , bf16_t* outbs  , const float* __restrict__ gate, ...
;     ...
;     const int r = tid >> 3, c8 = (tid & 7) * 8;
;     f32x4 s0 = {0.f, 0.f, 0.f, 0.f}, s1 = {0.f, 0.f, 0.f, 0.f};
; #pragma unroll
;     for (int w = 0; w < 8; ++w) { const LAS float* sp = (const LAS float*)lds + w * 4096 + r * 64 + c8; s0 += *(const LAS f32x4*)sp; s1 += *(const LAS f32x4*)(sp + 4); }
;     const int srow = row0 + r, nidx = NPB + (srow >> 3);
;     const size_t ro = (size_t)srow * D + col0 + c8; const float* gp = gate + (size_t)nidx * 3072 + col0 + c8;
;     const f32x4 g0 = *(const f32x4*)gp, g1 = *(const f32x4*)(gp + 4);
;     f32x4 x0, x1;
;     if (xs) { x0 = *(const f32x4*)(xs + ro); x1 = *(const f32x4*)(xs + ro + 4); }
;     else { const u32x4 w = __builtin_nontemporal_load((const u32x4*)(xbs + ro));
;         x0 = (f32x4){__uint_as_float(w.x << 16), __uint_as_float(w.x & 0xffff0000u), __uint_as_float(w.y << 16), __uint_as_float(w.y & 0xffff0000u)};
;         x1 = (f32x4){__uint_as_float(w.z << 16), __uint_as_float(w.z & 0xffff0000u), __uint_as_float(w.w << 16), __uint_as_float(w.w & 0xffff0000u)}; }
;     const f32x4 v0 = x0 + g0 * s0, v1 = x1 + g1 * s1;
;     if (outbs) { u32x4 w; w.x = pk_bf16(v0[0], v0[1]); w.y = pk_bf16(v0[2], v0[3]); w.z = pk_bf16(v1[0], v1[1]); w.w = pk_bf16(v1[2], v1[3]); *(u32x4*)(outbs + ro) = w; }
;     else { *(f32x4*)(outs + ro) = v0; *(f32x4*)(outs + ro + 4) = v1; }
	v_add_u32_e32 v0, s21, v80
	v_ashrrev_i32_e32 v1, 3, v0
	v_add_u32_e32 v2, 4, v1
	v_ashrrev_i32_e32 v1, 31, v0
	v_lshlrev_b64 v[16:17], 10, v[0:1]
	v_or_b32_e32 v0, s20, v16
	v_or_b32_e32 v16, v0, v68
	v_mov_b64_e32 v[0:1], s[4:5]
	s_movk_i32 s21, 0x3000
	v_mad_i64_i32 v[0:1], s[26:27], v2, s21, v[0:1]
	v_lshl_add_u64 v[0:1], v[0:1], 0, s[86:87]
	v_lshl_add_u64 v[4:5], v[0:1], 0, v[172:173]
	v_lshl_add_u64 v[18:19], v[16:17], 1, s[10:11]
	global_load_dwordx4 v[106:109], v[4:5], off offset:16
	global_load_dwordx4 v[110:113], v[4:5], off
	global_load_dwordx4 v[114:117], v[18:19], off
	ds_read_b128 v[20:23], v81
	ds_read_b128 v[24:27], v81 offset:16
	ds_read_b128 v[28:31], v81 offset:16384
	ds_read_b128 v[32:35], v81 offset:16400
	ds_read_b128 v[36:39], v81 offset:32768
	ds_read_b128 v[40:43], v81 offset:32784
	ds_read_b128 v[44:47], v81 offset:49152
	ds_read_b128 v[48:51], v81 offset:49168
	ds_read_b128 v[52:55], v82
	ds_read_b128 v[56:59], v83
	ds_read_b128 v[60:63], v84
	ds_read_b128 v[90:93], v85
	ds_read_b128 v[94:97], v86
	ds_read_b128 v[98:101], v87
	ds_read_b128 v[102:105], v88
	ds_read_b128 v[118:121], v89
	v_readlane_b32 s26, v255, 8
	v_readlane_b32 s27, v255, 9
	s_mov_b64 s[20:21], -1
	s_waitcnt lgkmcnt(14)
	v_pk_add_f32 v[8:9], v[22:23], 0 op_sel_hi:[1,0]
	v_pk_add_f32 v[10:11], v[20:21], 0 op_sel_hi:[1,0]
	v_pk_add_f32 v[6:7], v[26:27], 0 op_sel_hi:[1,0]
	v_pk_add_f32 v[4:5], v[24:25], 0 op_sel_hi:[1,0]
	s_waitcnt lgkmcnt(12)
	v_pk_add_f32 v[8:9], v[8:9], v[30:31]
	v_pk_add_f32 v[10:11], v[10:11], v[28:29]
	v_pk_add_f32 v[6:7], v[6:7], v[34:35]
	v_pk_add_f32 v[4:5], v[4:5], v[32:33]
	s_waitcnt lgkmcnt(10)
	v_pk_add_f32 v[8:9], v[8:9], v[38:39]
	v_pk_add_f32 v[10:11], v[10:11], v[36:37]
	v_pk_add_f32 v[6:7], v[6:7], v[42:43]
	v_pk_add_f32 v[4:5], v[4:5], v[40:41]
	s_waitcnt lgkmcnt(8)
	v_pk_add_f32 v[8:9], v[8:9], v[46:47]
	v_pk_add_f32 v[10:11], v[10:11], v[44:45]
	v_pk_add_f32 v[6:7], v[6:7], v[50:51]
	v_pk_add_f32 v[4:5], v[4:5], v[48:49]
	s_waitcnt lgkmcnt(6)
	v_pk_add_f32 v[8:9], v[8:9], v[54:55]
	v_pk_add_f32 v[10:11], v[10:11], v[52:53]
	v_pk_add_f32 v[6:7], v[6:7], v[58:59]
	v_pk_add_f32 v[4:5], v[4:5], v[56:57]
	s_waitcnt lgkmcnt(4)
	v_pk_add_f32 v[8:9], v[8:9], v[62:63]
	v_pk_add_f32 v[10:11], v[10:11], v[60:61]
	v_pk_add_f32 v[6:7], v[6:7], v[92:93]
	v_pk_add_f32 v[4:5], v[4:5], v[90:91]
	s_waitcnt lgkmcnt(2)
	v_pk_add_f32 v[8:9], v[8:9], v[96:97]
	v_pk_add_f32 v[10:11], v[10:11], v[94:95]
	v_pk_add_f32 v[6:7], v[6:7], v[100:101]
	v_pk_add_f32 v[4:5], v[4:5], v[98:99]
	s_waitcnt lgkmcnt(0)
	v_pk_add_f32 v[12:13], v[8:9], v[104:105]
	v_pk_add_f32 v[14:15], v[10:11], v[102:103]
	v_pk_add_f32 v[10:11], v[4:5], v[118:119]
	v_pk_add_f32 v[8:9], v[6:7], v[120:121]
	s_and_b64 vcc, exec, s[26:27]
	s_waitcnt vmcnt(0)
	v_lshlrev_b32_e32 v22, 16, v114
	v_and_b32_e32 v23, 0xffff0000, v114
	v_lshlrev_b32_e32 v18, 16, v115
	v_and_b32_e32 v19, 0xffff0000, v115
	v_lshlrev_b32_e32 v24, 16, v116
	v_and_b32_e32 v25, 0xffff0000, v116
	v_lshlrev_b32_e32 v20, 16, v117
	v_and_b32_e32 v21, 0xffff0000, v117
	v_pk_fma_f32 v[4:5], v[14:15], v[110:111], v[22:23]
	v_pk_fma_f32 v[6:7], v[12:13], v[112:113], v[18:19]
	v_pk_fma_f32 v[0:1], v[10:11], v[106:107], v[24:25]
	v_pk_fma_f32 v[2:3], v[8:9], v[108:109], v[20:21]
	s_cbranch_vccz .LBB0_596
	v_readlane_b32 s20, v254, 24
	v_readlane_b32 s21, v254, 25
	s_nop 1
	v_lshl_add_u64 v[8:9], v[16:17], 2, s[20:21]
	global_store_dwordx4 v[8:9], v[4:7], off sc1
	global_store_dwordx4 v[8:9], v[0:3], off offset:16 sc1
	s_mov_b64 s[20:21], 0

; __device__ __forceinline__ unsigned cvt_pk_bf16(float lo, float hi) { unsigned r; asm volatile("v_cvt_pk_bf16_f32 %0, %1, %2" : "=v"(r) : "v"(lo), "v"(hi)); return r; }
;     __device__ __forceinline__ void operator()(const f32x4 (&acc)[2][2][4][2], const Unit& u, int wr, int wc, int fr, int fq) const {
;     ...
;             for (int mi = 0; mi < 4; ++mi) { const bf16_t* bp = xb + (size_t)(u.pm * BM + ai * HALF + wr * 64 + mi * 16 + fr) * 1024 + col0;
; #pragma unroll
;                 for (int bj = 0; bj < 2; ++bj) xw[mi][bj] = __builtin_nontemporal_load((const u32x4*)(bp + bj * HALF)); }
; #pragma unroll
;             for (int mi = 0; mi < 4; ++mi) { const size_t ro = (size_t)(u.pm * BM + ai * HALF + wr * 64 + mi * 16 + fr) * 1024 + col0;
; #pragma unroll
;                 for (int bj = 0; bj < 2; ++bj) { const u32x4 w = xw[mi][bj];
;                     const f32x4 x0 = (f32x4){__uint_as_float(w.x << 16), __uint_as_float(w.x & 0xffff0000u), __uint_as_float(w.y << 16), __uint_as_float(w.y & 0xffff0000u)};
;                     const f32x4 x1 = (f32x4){__uint_as_float(w.z << 16), __uint_as_float(w.z & 0xffff0000u), __uint_as_float(w.w << 16), __uint_as_float(w.w & 0xffff0000u)};
;                     const f32x4 v0 = x0 + gv[bj][0] * acc[ai][bj][mi][0], v1 = x1 + gv[bj][1] * acc[ai][bj][mi][1];
;                     if (l0) { u32x4 o; o.x = cvt_pk_bf16(v0[0], v0[1]); o.y = cvt_pk_bf16(v0[2], v0[3]); o.z = cvt_pk_bf16(v1[0], v1[1]); o.w = cvt_pk_bf16(v1[2], v1[3]);
;                               *(u32x4*)(outb + ro + bj * HALF) = o; }
;                     else { __builtin_nontemporal_store(v0, (f32x4*)(outf + ro + bj * HALF)); __builtin_nontemporal_store(v1, (f32x4*)(outf + ro + bj * HALF + 4)); }
.LBB0_616:
	s_ashr_i32 s25, s61, 4
	v_lshl_or_b32 v192, s62, 8, v229
	s_mul_hi_i32 s27, s25, 0x3000
	s_mulk_i32 s25, 0x3000
	v_lshl_add_u32 v196, s61, 8, v227
	s_add_u32 s34, s4, s25
	v_ashrrev_i32_e32 v193, 31, v192
	v_ashrrev_i32_e32 v197, 31, v196
	s_addc_u32 s35, s5, s27
	v_lshl_add_u64 v[194:195], v[192:193], 1, s[6:7]
	v_lshlrev_b64 v[144:145], 11, v[196:197]
	v_or_b32_e32 v202, 16, v196
	v_lshl_add_u64 v[72:73], v[192:193], 2, s[34:35]
	v_lshl_add_u64 v[144:145], v[194:195], 0, v[144:145]
	v_ashrrev_i32_e32 v203, 31, v202
	global_load_dwordx4 v[80:83], v[72:73], off offset:16
	global_load_dwordx4 v[84:87], v[72:73], off
	global_load_dwordx4 v[68:71], v[72:73], off offset:528
	s_nop 0
	global_load_dwordx4 v[72:75], v[72:73], off offset:512
	s_nop 0
	global_load_dwordx4 v[236:239], v[144:145], off
	global_load_dwordx4 v[168:171], v[144:145], off offset:256
	v_lshlrev_b64 v[144:145], 11, v[202:203]
	v_or_b32_e32 v200, 32, v196
	v_lshl_add_u64 v[144:145], v[194:195], 0, v[144:145]
	v_ashrrev_i32_e32 v201, 31, v200
	global_load_dwordx4 v[164:167], v[144:145], off
	global_load_dwordx4 v[160:163], v[144:145], off offset:256
	v_lshlrev_b64 v[144:145], 11, v[200:201]
	v_or_b32_e32 v198, 48, v196
	v_lshl_add_u64 v[144:145], v[194:195], 0, v[144:145]
	v_ashrrev_i32_e32 v199, 31, v198
	global_load_dwordx4 v[156:159], v[144:145], off
	global_load_dwordx4 v[152:155], v[144:145], off offset:256
	v_lshlrev_b64 v[144:145], 11, v[198:199]
	v_lshl_add_u64 v[144:145], v[194:195], 0, v[144:145]
	global_load_dwordx4 v[148:151], v[144:145], off
	s_nop 0
	global_load_dwordx4 v[144:147], v[144:145], off offset:256
	v_lshlrev_b64 v[204:205], 10, v[196:197]
	v_lshl_add_u64 v[206:207], v[204:205], 0, v[192:193]
	s_mov_b64 s[34:35], -1
	s_andn2_b64 vcc, exec, s[8:9]
	s_waitcnt vmcnt(0)
	v_lshlrev_b32_e32 v204, 16, v236
	v_and_b32_e32 v205, 0xffff0000, v236
	v_lshlrev_b32_e32 v210, 16, v237
	v_and_b32_e32 v211, 0xffff0000, v237
	v_lshlrev_b32_e32 v236, 16, v238
	v_and_b32_e32 v237, 0xffff0000, v238
	v_lshlrev_b32_e32 v238, 16, v239
	v_and_b32_e32 v239, 0xffff0000, v239
	v_pk_fma_f32 v[142:143], v[142:143], v[86:87], v[210:211]
	v_pk_fma_f32 v[140:141], v[140:141], v[84:85], v[204:205]
	v_pk_fma_f32 v[138:139], v[138:139], v[82:83], v[238:239]
	v_pk_fma_f32 v[136:137], v[136:137], v[80:81], v[236:237]
	v_lshl_add_u64 v[204:205], v[206:207], 1, s[58:59]
	s_cbranch_vccnz .LBB0_618
	s_mov_b64 s[34:35], 0
	v_cvt_pk_bf16_f32 v236, v140, v141
	v_cvt_pk_bf16_f32 v237, v142, v143
	v_cvt_pk_bf16_f32 v238, v136, v137
	v_cvt_pk_bf16_f32 v239, v138, v139
	global_store_dwordx4 v[204:205], v[236:239], off sc1

; __device__ __forceinline__ unsigned cvt_pk_bf16(float lo, float hi) { unsigned r; asm volatile("v_cvt_pk_bf16_f32 %0, %1, %2" : "=v"(r) : "v"(lo), "v"(hi)); return r; }
;     __device__ __forceinline__ void operator()(const f32x4 (&acc)[2][2][4][2], const Unit& u, int wr, int wc, int fr, int fq) const {
;     ...
;             for (int mi = 0; mi < 4; ++mi) { const bf16_t* bp = xb + (size_t)(u.pm * BM + ai * HALF + wr * 64 + mi * 16 + fr) * 1024 + col0;
; #pragma unroll
;                 for (int bj = 0; bj < 2; ++bj) xw[mi][bj] = __builtin_nontemporal_load((const u32x4*)(bp + bj * HALF)); }
; #pragma unroll
;             for (int mi = 0; mi < 4; ++mi) { const size_t ro = (size_t)(u.pm * BM + ai * HALF + wr * 64 + mi * 16 + fr) * 1024 + col0;
; #pragma unroll
;                 for (int bj = 0; bj < 2; ++bj) { const u32x4 w = xw[mi][bj];
;                     const f32x4 x0 = (f32x4){__uint_as_float(w.x << 16), __uint_as_float(w.x & 0xffff0000u), __uint_as_float(w.y << 16), __uint_as_float(w.y & 0xffff0000u)};
;                     const f32x4 x1 = (f32x4){__uint_as_float(w.z << 16), __uint_as_float(w.z & 0xffff0000u), __uint_as_float(w.w << 16), __uint_as_float(w.w & 0xffff0000u)};
;                     const f32x4 v0 = x0 + gv[bj][0] * acc[ai][bj][mi][0], v1 = x1 + gv[bj][1] * acc[ai][bj][mi][1];
;                     if (l0) { u32x4 o; o.x = cvt_pk_bf16(v0[0], v0[1]); o.y = cvt_pk_bf16(v0[2], v0[3]); o.z = cvt_pk_bf16(v1[0], v1[1]); o.w = cvt_pk_bf16(v1[2], v1[3]);
;                               *(u32x4*)(outb + ro + bj * HALF) = o; }
;                     else { __builtin_nontemporal_store(v0, (f32x4*)(outf + ro + bj * HALF)); __builtin_nontemporal_store(v1, (f32x4*)(outf + ro + bj * HALF + 4)); }
.LBB0_648:
	v_add_u32_e32 v114, 0x80, v196
	v_ashrrev_i32_e32 v115, 31, v114
	v_lshlrev_b64 v[64:65], 11, v[114:115]
	v_add_u32_e32 v112, 0x90, v196
	v_lshl_add_u64 v[64:65], v[194:195], 0, v[64:65]
	v_ashrrev_i32_e32 v113, 31, v112
	global_load_dwordx4 v[116:119], v[64:65], off
	global_load_dwordx4 v[104:107], v[64:65], off offset:256
	v_lshlrev_b64 v[64:65], 11, v[112:113]
	v_add_u32_e32 v110, 0xa0, v196
	v_lshl_add_u64 v[64:65], v[194:195], 0, v[64:65]
	v_ashrrev_i32_e32 v111, 31, v110
	global_load_dwordx4 v[100:103], v[64:65], off
	global_load_dwordx4 v[96:99], v[64:65], off offset:256
	v_lshlrev_b64 v[64:65], 11, v[110:111]
	v_add_u32_e32 v108, 0xb0, v196
	v_lshl_add_u64 v[64:65], v[194:195], 0, v[64:65]
	v_ashrrev_i32_e32 v109, 31, v108
	global_load_dwordx4 v[92:95], v[64:65], off
	global_load_dwordx4 v[88:91], v[64:65], off offset:256
	v_lshlrev_b64 v[64:65], 11, v[108:109]
	v_lshl_add_u64 v[64:65], v[194:195], 0, v[64:65]
	global_load_dwordx4 v[76:79], v[64:65], off
	s_nop 0
	global_load_dwordx4 v[64:67], v[64:65], off offset:256
	v_lshlrev_b64 v[114:115], 10, v[114:115]
	v_lshl_add_u64 v[114:115], v[114:115], 0, v[192:193]
	s_mov_b64 s[34:35], -1
	s_and_b64 vcc, exec, s[8:9]
	s_waitcnt vmcnt(7)
	v_lshlrev_b32_e32 v120, 16, v116
	v_and_b32_e32 v121, 0xffff0000, v116
	v_lshlrev_b32_e32 v116, 16, v117
	v_and_b32_e32 v117, 0xffff0000, v117
	v_lshlrev_b32_e32 v122, 16, v118
	v_and_b32_e32 v123, 0xffff0000, v118
	v_lshlrev_b32_e32 v118, 16, v119
	v_and_b32_e32 v119, 0xffff0000, v119
	v_pk_fma_f32 v[62:63], v[62:63], v[86:87], v[116:117]
	v_pk_fma_f32 v[60:61], v[60:61], v[84:85], v[120:121]
	v_pk_fma_f32 v[58:59], v[58:59], v[82:83], v[118:119]
	v_pk_fma_f32 v[56:57], v[56:57], v[80:81], v[122:123]
	v_lshl_add_u64 v[116:117], v[114:115], 1, s[58:59]
	s_cbranch_vccz .LBB0_650
	v_cvt_pk_bf16_f32 v118, v60, v61
	v_cvt_pk_bf16_f32 v119, v62, v63
	v_cvt_pk_bf16_f32 v120, v56, v57
	v_cvt_pk_bf16_f32 v121, v58, v59
	global_store_dwordx4 v[116:117], v[118:121], off sc1
	s_mov_b64 s[34:35], 0
